# opt14c + G5 mid-product gate scaling regenerated: gate loads four steps ahead (ring of 4 buffers, SGPR-base addressing, counted vmcnt) instead of a 16-step vmcnt(0) ladder
# speedup vs baseline: 1.0215x; 1.0140x over previous
; __device__ __forceinline__ float bf_lo(unsigned w) { return __uint_as_float(w << 16); }
; __device__ __forceinline__ float bf_hi(unsigned w) { return __uint_as_float(w & 0xffff0000u); }
;     __device__ __forceinline__ void mid(Acc& acc, const Unit& u, int wr, int wc, int fr, int fq) const {
;         int row0 = u.pm * BM + wr * 64 + fr; const int col0 = u.pn * BM + wc * 32 + 8 * fq;
;         asm volatile("" : "+v"(row0));
; #pragma unroll
;         for (int ai = 0; ai < 2; ++ai)
; #pragma unroll
;             for (int m = 0; m < 4; ++m) {
;                 const int row = row0 + ai * HALF + m * 16;
; #pragma unroll
;                 for (int bj = 0; bj < 2; ++bj) {
;                     const int col = col0 + bj * HALF;
;                     const u32x4 ga = *(const u32x4*)(P + (size_t)row * PP + C_GA + col), gb = *(const u32x4*)(P + (size_t)row * PP + C_GB + col);
;                     const float ra[8] = {bf_lo(ga.x), bf_hi(ga.x), bf_lo(ga.y), bf_hi(ga.y), bf_lo(ga.z), bf_hi(ga.z), bf_lo(ga.w), bf_hi(ga.w)};
;                     const float rb[8] = {bf_lo(gb.x), bf_hi(gb.x), bf_lo(gb.y), bf_hi(gb.y), bf_lo(gb.z), bf_hi(gb.z), bf_lo(gb.w), bf_hi(gb.w)};
; #pragma unroll
;                     for (int n = 0; n < 2; ++n)
; #pragma unroll
;                         for (int e = 0; e < 4; ++e) acc[ai][bj][m][n][e] *= ra[4 * n + e] * __builtin_amdgcn_rcpf(rb[4 * n + e]);
;                 }
;                 asm volatile("" ::: "memory");
;             }
;     }
.LBB0_1084:
	s_cmpk_lg_i32 s54, 0x800
	s_cbranch_scc1 .LBB0_1083
	v_lshlrev_b32_e32 v183, 1, v156
	v_lshl_add_u32 v183, v152, 13, v183
	s_add_u32 s56, s20, 0x1000
	s_addc_u32 s57, s21, 0
	global_load_dwordx4 v[184:187], v183, s[56:57]
	global_load_dwordx4 v[188:191], v183, s[56:57] offset:2048
	global_load_dwordx4 v[192:195], v183, s[56:57] offset:256
	global_load_dwordx4 v[196:199], v183, s[56:57] offset:2304
	s_add_u32 s56, s20, 0x21000
	s_addc_u32 s57, s21, 0
	global_load_dwordx4 v[200:203], v183, s[56:57]
	global_load_dwordx4 v[204:207], v183, s[56:57] offset:2048
	global_load_dwordx4 v[208:211], v183, s[56:57] offset:256
	global_load_dwordx4 v[212:215], v183, s[56:57] offset:2304
	s_waitcnt vmcnt(6)
	v_lshlrev_b32_e32 v216, 16, v188
	v_and_b32_e32 v217, 0xffff0000, v188
	v_lshlrev_b32_e32 v218, 16, v189
	v_and_b32_e32 v219, 0xffff0000, v189
	v_lshlrev_b32_e32 v220, 16, v190
	v_and_b32_e32 v221, 0xffff0000, v190
	v_lshlrev_b32_e32 v222, 16, v191
	v_and_b32_e32 v223, 0xffff0000, v191
	v_rcp_f32_e32 v216, v216
	v_rcp_f32_e32 v217, v217
	v_rcp_f32_e32 v218, v218
	v_rcp_f32_e32 v219, v219
	v_rcp_f32_e32 v220, v220
	v_rcp_f32_e32 v221, v221
	v_rcp_f32_e32 v222, v222
	v_rcp_f32_e32 v223, v223
	v_lshlrev_b32_e32 v224, 16, v184
	v_and_b32_e32 v225, 0xffff0000, v184
	v_lshlrev_b32_e32 v226, 16, v185
	v_and_b32_e32 v227, 0xffff0000, v185
	v_lshlrev_b32_e32 v228, 16, v186
	v_and_b32_e32 v229, 0xffff0000, v186
	v_lshlrev_b32_e32 v230, 16, v187
	v_and_b32_e32 v231, 0xffff0000, v187
	s_add_u32 s56, s20, 0x41000
	s_addc_u32 s57, s21, 0
	global_load_dwordx4 v[184:187], v183, s[56:57]
	global_load_dwordx4 v[188:191], v183, s[56:57] offset:2048
	v_mul_f32_e32 v216, v216, v224
	v_mul_f32_e32 v217, v217, v225
	v_mul_f32_e32 v218, v218, v226
	v_mul_f32_e32 v219, v219, v227
	v_mul_f32_e32 v220, v220, v228
	v_mul_f32_e32 v221, v221, v229
	v_mul_f32_e32 v222, v222, v230
	v_mul_f32_e32 v223, v223, v231
	v_mul_f32_e32 v124, v124, v216
	v_mul_f32_e32 v125, v125, v217
	v_mul_f32_e32 v126, v126, v218
	v_mul_f32_e32 v127, v127, v219
	v_mul_f32_e32 v120, v120, v220
	v_mul_f32_e32 v121, v121, v221
	v_mul_f32_e32 v122, v122, v222
	v_mul_f32_e32 v123, v123, v223
	s_waitcnt vmcnt(6)
	v_lshlrev_b32_e32 v216, 16, v196
	v_and_b32_e32 v217, 0xffff0000, v196
	v_lshlrev_b32_e32 v218, 16, v197
	v_and_b32_e32 v219, 0xffff0000, v197
	v_lshlrev_b32_e32 v220, 16, v198
	v_and_b32_e32 v221, 0xffff0000, v198
	v_lshlrev_b32_e32 v222, 16, v199
	v_and_b32_e32 v223, 0xffff0000, v199
	v_rcp_f32_e32 v216, v216
	v_rcp_f32_e32 v217, v217
	v_rcp_f32_e32 v218, v218
	v_rcp_f32_e32 v219, v219
	v_rcp_f32_e32 v220, v220
	v_rcp_f32_e32 v221, v221
	v_rcp_f32_e32 v222, v222
	v_rcp_f32_e32 v223, v223
	v_lshlrev_b32_e32 v224, 16, v192
	v_and_b32_e32 v225, 0xffff0000, v192
	v_lshlrev_b32_e32 v226, 16, v193
	v_and_b32_e32 v227, 0xffff0000, v193
	v_lshlrev_b32_e32 v228, 16, v194
	v_and_b32_e32 v229, 0xffff0000, v194
	v_lshlrev_b32_e32 v230, 16, v195
	v_and_b32_e32 v231, 0xffff0000, v195
	global_load_dwordx4 v[192:195], v183, s[56:57] offset:256
	global_load_dwordx4 v[196:199], v183, s[56:57] offset:2304
	v_mul_f32_e32 v216, v216, v224
	v_mul_f32_e32 v217, v217, v225
	v_mul_f32_e32 v218, v218, v226
	v_mul_f32_e32 v219, v219, v227
	v_mul_f32_e32 v220, v220, v228
	v_mul_f32_e32 v221, v221, v229
	v_mul_f32_e32 v222, v222, v230
	v_mul_f32_e32 v223, v223, v231
	v_mul_f32_e32 v116, v116, v216
	v_mul_f32_e32 v117, v117, v217
	v_mul_f32_e32 v118, v118, v218
	v_mul_f32_e32 v119, v119, v219
	v_mul_f32_e32 v112, v112, v220
	v_mul_f32_e32 v113, v113, v221
	v_mul_f32_e32 v114, v114, v222
	v_mul_f32_e32 v115, v115, v223
	s_waitcnt vmcnt(6)
	v_lshlrev_b32_e32 v216, 16, v204
	v_and_b32_e32 v217, 0xffff0000, v204
	v_lshlrev_b32_e32 v218, 16, v205
	v_and_b32_e32 v219, 0xffff0000, v205
	v_lshlrev_b32_e32 v220, 16, v206
	v_and_b32_e32 v221, 0xffff0000, v206
	v_lshlrev_b32_e32 v222, 16, v207
	v_and_b32_e32 v223, 0xffff0000, v207
	v_rcp_f32_e32 v216, v216
	v_rcp_f32_e32 v217, v217
	v_rcp_f32_e32 v218, v218
	v_rcp_f32_e32 v219, v219
	v_rcp_f32_e32 v220, v220
	v_rcp_f32_e32 v221, v221
	v_rcp_f32_e32 v222, v222
	v_rcp_f32_e32 v223, v223
	v_lshlrev_b32_e32 v224, 16, v200
	v_and_b32_e32 v225, 0xffff0000, v200
	v_lshlrev_b32_e32 v226, 16, v201
	v_and_b32_e32 v227, 0xffff0000, v201
	v_lshlrev_b32_e32 v228, 16, v202
	v_and_b32_e32 v229, 0xffff0000, v202
	v_lshlrev_b32_e32 v230, 16, v203
	v_and_b32_e32 v231, 0xffff0000, v203
	s_add_u32 s56, s20, 0x61000
	s_addc_u32 s57, s21, 0
	global_load_dwordx4 v[200:203], v183, s[56:57]
	global_load_dwordx4 v[204:207], v183, s[56:57] offset:2048
	v_mul_f32_e32 v216, v216, v224
	v_mul_f32_e32 v217, v217, v225
	v_mul_f32_e32 v218, v218, v226
	v_mul_f32_e32 v219, v219, v227
	v_mul_f32_e32 v220, v220, v228
	v_mul_f32_e32 v221, v221, v229
	v_mul_f32_e32 v222, v222, v230
	v_mul_f32_e32 v223, v223, v231
	v_mul_f32_e32 v108, v108, v216
	v_mul_f32_e32 v109, v109, v217
	v_mul_f32_e32 v110, v110, v218
	v_mul_f32_e32 v111, v111, v219
	v_mul_f32_e32 v104, v104, v220
	v_mul_f32_e32 v105, v105, v221
	v_mul_f32_e32 v106, v106, v222
	v_mul_f32_e32 v107, v107, v223
	s_waitcnt vmcnt(6)
; __device__ __forceinline__ float bf_lo(unsigned w) { return __uint_as_float(w << 16); }
; __device__ __forceinline__ float bf_hi(unsigned w) { return __uint_as_float(w & 0xffff0000u); }
;     __device__ __forceinline__ void mid(Acc& acc, const Unit& u, int wr, int wc, int fr, int fq) const {
;         int row0 = u.pm * BM + wr * 64 + fr; const int col0 = u.pn * BM + wc * 32 + 8 * fq;
;         asm volatile("" : "+v"(row0));
; #pragma unroll
;         for (int ai = 0; ai < 2; ++ai)
; #pragma unroll
;             for (int m = 0; m < 4; ++m) {
;                 const int row = row0 + ai * HALF + m * 16;
; #pragma unroll
;                 for (int bj = 0; bj < 2; ++bj) {
;                     const int col = col0 + bj * HALF;
;                     const u32x4 ga = *(const u32x4*)(P + (size_t)row * PP + C_GA + col), gb = *(const u32x4*)(P + (size_t)row * PP + C_GB + col);
;                     const float ra[8] = {bf_lo(ga.x), bf_hi(ga.x), bf_lo(ga.y), bf_hi(ga.y), bf_lo(ga.z), bf_hi(ga.z), bf_lo(ga.w), bf_hi(ga.w)};
;                     const float rb[8] = {bf_lo(gb.x), bf_hi(gb.x), bf_lo(gb.y), bf_hi(gb.y), bf_lo(gb.z), bf_hi(gb.z), bf_lo(gb.w), bf_hi(gb.w)};
; #pragma unroll
;                     for (int n = 0; n < 2; ++n)
; #pragma unroll
;                         for (int e = 0; e < 4; ++e) acc[ai][bj][m][n][e] *= ra[4 * n + e] * __builtin_amdgcn_rcpf(rb[4 * n + e]);
;                 }
;                 asm volatile("" ::: "memory");
;             }
;     }
	v_lshlrev_b32_e32 v216, 16, v212
	v_and_b32_e32 v217, 0xffff0000, v212
	v_lshlrev_b32_e32 v218, 16, v213
	v_and_b32_e32 v219, 0xffff0000, v213
	v_lshlrev_b32_e32 v220, 16, v214
	v_and_b32_e32 v221, 0xffff0000, v214
	v_lshlrev_b32_e32 v222, 16, v215
	v_and_b32_e32 v223, 0xffff0000, v215
	v_rcp_f32_e32 v216, v216
	v_rcp_f32_e32 v217, v217
	v_rcp_f32_e32 v218, v218
	v_rcp_f32_e32 v219, v219
	v_rcp_f32_e32 v220, v220
	v_rcp_f32_e32 v221, v221
	v_rcp_f32_e32 v222, v222
	v_rcp_f32_e32 v223, v223
	v_lshlrev_b32_e32 v224, 16, v208
	v_and_b32_e32 v225, 0xffff0000, v208
	v_lshlrev_b32_e32 v226, 16, v209
	v_and_b32_e32 v227, 0xffff0000, v209
	v_lshlrev_b32_e32 v228, 16, v210
	v_and_b32_e32 v229, 0xffff0000, v210
	v_lshlrev_b32_e32 v230, 16, v211
	v_and_b32_e32 v231, 0xffff0000, v211
	global_load_dwordx4 v[208:211], v183, s[56:57] offset:256
	global_load_dwordx4 v[212:215], v183, s[56:57] offset:2304
	v_mul_f32_e32 v216, v216, v224
	v_mul_f32_e32 v217, v217, v225
	v_mul_f32_e32 v218, v218, v226
	v_mul_f32_e32 v219, v219, v227
	v_mul_f32_e32 v220, v220, v228
	v_mul_f32_e32 v221, v221, v229
	v_mul_f32_e32 v222, v222, v230
	v_mul_f32_e32 v223, v223, v231
	v_mul_f32_e32 v100, v100, v216
	v_mul_f32_e32 v101, v101, v217
	v_mul_f32_e32 v102, v102, v218
	v_mul_f32_e32 v103, v103, v219
	v_mul_f32_e32 v96, v96, v220
	v_mul_f32_e32 v97, v97, v221
	v_mul_f32_e32 v98, v98, v222
	v_mul_f32_e32 v99, v99, v223
	s_waitcnt vmcnt(6)
	v_lshlrev_b32_e32 v216, 16, v188
	v_and_b32_e32 v217, 0xffff0000, v188
	v_lshlrev_b32_e32 v218, 16, v189
	v_and_b32_e32 v219, 0xffff0000, v189
	v_lshlrev_b32_e32 v220, 16, v190
	v_and_b32_e32 v221, 0xffff0000, v190
	v_lshlrev_b32_e32 v222, 16, v191
	v_and_b32_e32 v223, 0xffff0000, v191
	v_rcp_f32_e32 v216, v216
	v_rcp_f32_e32 v217, v217
	v_rcp_f32_e32 v218, v218
	v_rcp_f32_e32 v219, v219
	v_rcp_f32_e32 v220, v220
	v_rcp_f32_e32 v221, v221
	v_rcp_f32_e32 v222, v222
	v_rcp_f32_e32 v223, v223
	v_lshlrev_b32_e32 v224, 16, v184
	v_and_b32_e32 v225, 0xffff0000, v184
	v_lshlrev_b32_e32 v226, 16, v185
	v_and_b32_e32 v227, 0xffff0000, v185
	v_lshlrev_b32_e32 v228, 16, v186
	v_and_b32_e32 v229, 0xffff0000, v186
	v_lshlrev_b32_e32 v230, 16, v187
	v_and_b32_e32 v231, 0xffff0000, v187
	s_add_u32 s56, s20, 0x101000
	s_addc_u32 s57, s21, 0
	global_load_dwordx4 v[184:187], v183, s[56:57]
	global_load_dwordx4 v[188:191], v183, s[56:57] offset:2048
	v_mul_f32_e32 v216, v216, v224
	v_mul_f32_e32 v217, v217, v225
	v_mul_f32_e32 v218, v218, v226
	v_mul_f32_e32 v219, v219, v227
	v_mul_f32_e32 v220, v220, v228
	v_mul_f32_e32 v221, v221, v229
	v_mul_f32_e32 v222, v222, v230
	v_mul_f32_e32 v223, v223, v231
	v_mul_f32_e32 v92, v92, v216
	v_mul_f32_e32 v93, v93, v217
	v_mul_f32_e32 v94, v94, v218
	v_mul_f32_e32 v95, v95, v219
	v_mul_f32_e32 v88, v88, v220
	v_mul_f32_e32 v89, v89, v221
	v_mul_f32_e32 v90, v90, v222
	v_mul_f32_e32 v91, v91, v223
	s_waitcnt vmcnt(6)
	v_lshlrev_b32_e32 v216, 16, v196
	v_and_b32_e32 v217, 0xffff0000, v196
	v_lshlrev_b32_e32 v218, 16, v197
	v_and_b32_e32 v219, 0xffff0000, v197
	v_lshlrev_b32_e32 v220, 16, v198
	v_and_b32_e32 v221, 0xffff0000, v198
	v_lshlrev_b32_e32 v222, 16, v199
	v_and_b32_e32 v223, 0xffff0000, v199
	v_rcp_f32_e32 v216, v216
	v_rcp_f32_e32 v217, v217
	v_rcp_f32_e32 v218, v218
	v_rcp_f32_e32 v219, v219
	v_rcp_f32_e32 v220, v220
	v_rcp_f32_e32 v221, v221
	v_rcp_f32_e32 v222, v222
	v_rcp_f32_e32 v223, v223
	v_lshlrev_b32_e32 v224, 16, v192
	v_and_b32_e32 v225, 0xffff0000, v192
	v_lshlrev_b32_e32 v226, 16, v193
	v_and_b32_e32 v227, 0xffff0000, v193
	v_lshlrev_b32_e32 v228, 16, v194
	v_and_b32_e32 v229, 0xffff0000, v194
	v_lshlrev_b32_e32 v230, 16, v195
	v_and_b32_e32 v231, 0xffff0000, v195
	global_load_dwordx4 v[192:195], v183, s[56:57] offset:256
	global_load_dwordx4 v[196:199], v183, s[56:57] offset:2304
	v_mul_f32_e32 v216, v216, v224
	v_mul_f32_e32 v217, v217, v225
	v_mul_f32_e32 v218, v218, v226
	v_mul_f32_e32 v219, v219, v227
	v_mul_f32_e32 v220, v220, v228
	v_mul_f32_e32 v221, v221, v229
	v_mul_f32_e32 v222, v222, v230
	v_mul_f32_e32 v223, v223, v231
	v_mul_f32_e32 v84, v84, v216
	v_mul_f32_e32 v85, v85, v217
	v_mul_f32_e32 v86, v86, v218
	v_mul_f32_e32 v87, v87, v219
	v_mul_f32_e32 v80, v80, v220
	v_mul_f32_e32 v81, v81, v221
	v_mul_f32_e32 v82, v82, v222
	v_mul_f32_e32 v83, v83, v223
	s_waitcnt vmcnt(6)
	v_lshlrev_b32_e32 v216, 16, v204
	v_and_b32_e32 v217, 0xffff0000, v204
	v_lshlrev_b32_e32 v218, 16, v205
	v_and_b32_e32 v219, 0xffff0000, v205
	v_lshlrev_b32_e32 v220, 16, v206
	v_and_b32_e32 v221, 0xffff0000, v206
	v_lshlrev_b32_e32 v222, 16, v207
	v_and_b32_e32 v223, 0xffff0000, v207
	v_rcp_f32_e32 v216, v216
	v_rcp_f32_e32 v217, v217
	v_rcp_f32_e32 v218, v218
	v_rcp_f32_e32 v219, v219
	v_rcp_f32_e32 v220, v220
	v_rcp_f32_e32 v221, v221
	v_rcp_f32_e32 v222, v222
	v_rcp_f32_e32 v223, v223
	v_lshlrev_b32_e32 v224, 16, v200
	v_and_b32_e32 v225, 0xffff0000, v200
	v_lshlrev_b32_e32 v226, 16, v201
	v_and_b32_e32 v227, 0xffff0000, v201
	v_lshlrev_b32_e32 v228, 16, v202
	v_and_b32_e32 v229, 0xffff0000, v202
	v_lshlrev_b32_e32 v230, 16, v203
	v_and_b32_e32 v231, 0xffff0000, v203
	s_add_u32 s56, s20, 0x121000
	s_addc_u32 s57, s21, 0
	global_load_dwordx4 v[200:203], v183, s[56:57]
	global_load_dwordx4 v[204:207], v183, s[56:57] offset:2048
	v_mul_f32_e32 v216, v216, v224
	v_mul_f32_e32 v217, v217, v225
	v_mul_f32_e32 v218, v218, v226
	v_mul_f32_e32 v219, v219, v227
	v_mul_f32_e32 v220, v220, v228
	v_mul_f32_e32 v221, v221, v229
	v_mul_f32_e32 v222, v222, v230
	v_mul_f32_e32 v223, v223, v231
	v_mul_f32_e32 v76, v76, v216
	v_mul_f32_e32 v77, v77, v217
	v_mul_f32_e32 v78, v78, v218
	v_mul_f32_e32 v79, v79, v219
	v_mul_f32_e32 v72, v72, v220
	v_mul_f32_e32 v73, v73, v221
	v_mul_f32_e32 v74, v74, v222
	v_mul_f32_e32 v75, v75, v223
	s_waitcnt vmcnt(6)
; __device__ __forceinline__ float bf_lo(unsigned w) { return __uint_as_float(w << 16); }
; __device__ __forceinline__ float bf_hi(unsigned w) { return __uint_as_float(w & 0xffff0000u); }
;     __device__ __forceinline__ void mid(Acc& acc, const Unit& u, int wr, int wc, int fr, int fq) const {
;         int row0 = u.pm * BM + wr * 64 + fr; const int col0 = u.pn * BM + wc * 32 + 8 * fq;
;         asm volatile("" : "+v"(row0));
; #pragma unroll
;         for (int ai = 0; ai < 2; ++ai)
; #pragma unroll
;             for (int m = 0; m < 4; ++m) {
;                 const int row = row0 + ai * HALF + m * 16;
; #pragma unroll
;                 for (int bj = 0; bj < 2; ++bj) {
;                     const int col = col0 + bj * HALF;
;                     const u32x4 ga = *(const u32x4*)(P + (size_t)row * PP + C_GA + col), gb = *(const u32x4*)(P + (size_t)row * PP + C_GB + col);
;                     const float ra[8] = {bf_lo(ga.x), bf_hi(ga.x), bf_lo(ga.y), bf_hi(ga.y), bf_lo(ga.z), bf_hi(ga.z), bf_lo(ga.w), bf_hi(ga.w)};
;                     const float rb[8] = {bf_lo(gb.x), bf_hi(gb.x), bf_lo(gb.y), bf_hi(gb.y), bf_lo(gb.z), bf_hi(gb.z), bf_lo(gb.w), bf_hi(gb.w)};
; #pragma unroll
;                     for (int n = 0; n < 2; ++n)
; #pragma unroll
;                         for (int e = 0; e < 4; ++e) acc[ai][bj][m][n][e] *= ra[4 * n + e] * __builtin_amdgcn_rcpf(rb[4 * n + e]);
;                 }
;                 asm volatile("" ::: "memory");
;             }
;     }
	v_lshlrev_b32_e32 v216, 16, v212
	v_and_b32_e32 v217, 0xffff0000, v212
	v_lshlrev_b32_e32 v218, 16, v213
	v_and_b32_e32 v219, 0xffff0000, v213
	v_lshlrev_b32_e32 v220, 16, v214
	v_and_b32_e32 v221, 0xffff0000, v214
	v_lshlrev_b32_e32 v222, 16, v215
	v_and_b32_e32 v223, 0xffff0000, v215
	v_rcp_f32_e32 v216, v216
	v_rcp_f32_e32 v217, v217
	v_rcp_f32_e32 v218, v218
	v_rcp_f32_e32 v219, v219
	v_rcp_f32_e32 v220, v220
	v_rcp_f32_e32 v221, v221
	v_rcp_f32_e32 v222, v222
	v_rcp_f32_e32 v223, v223
	v_lshlrev_b32_e32 v224, 16, v208
	v_and_b32_e32 v225, 0xffff0000, v208
	v_lshlrev_b32_e32 v226, 16, v209
	v_and_b32_e32 v227, 0xffff0000, v209
	v_lshlrev_b32_e32 v228, 16, v210
	v_and_b32_e32 v229, 0xffff0000, v210
	v_lshlrev_b32_e32 v230, 16, v211
	v_and_b32_e32 v231, 0xffff0000, v211
	global_load_dwordx4 v[208:211], v183, s[56:57] offset:256
	global_load_dwordx4 v[212:215], v183, s[56:57] offset:2304
	v_mul_f32_e32 v216, v216, v224
	v_mul_f32_e32 v217, v217, v225
	v_mul_f32_e32 v218, v218, v226
	v_mul_f32_e32 v219, v219, v227
	v_mul_f32_e32 v220, v220, v228
	v_mul_f32_e32 v221, v221, v229
	v_mul_f32_e32 v222, v222, v230
	v_mul_f32_e32 v223, v223, v231
	v_mul_f32_e32 v68, v68, v216
	v_mul_f32_e32 v69, v69, v217
	v_mul_f32_e32 v70, v70, v218
	v_mul_f32_e32 v71, v71, v219
	v_mul_f32_e32 v64, v64, v220
	v_mul_f32_e32 v65, v65, v221
	v_mul_f32_e32 v66, v66, v222
	v_mul_f32_e32 v67, v67, v223
	s_waitcnt vmcnt(6)
	v_lshlrev_b32_e32 v216, 16, v188
	v_and_b32_e32 v217, 0xffff0000, v188
	v_lshlrev_b32_e32 v218, 16, v189
	v_and_b32_e32 v219, 0xffff0000, v189
	v_lshlrev_b32_e32 v220, 16, v190
	v_and_b32_e32 v221, 0xffff0000, v190
	v_lshlrev_b32_e32 v222, 16, v191
	v_and_b32_e32 v223, 0xffff0000, v191
	v_rcp_f32_e32 v216, v216
	v_rcp_f32_e32 v217, v217
	v_rcp_f32_e32 v218, v218
	v_rcp_f32_e32 v219, v219
	v_rcp_f32_e32 v220, v220
	v_rcp_f32_e32 v221, v221
	v_rcp_f32_e32 v222, v222
	v_rcp_f32_e32 v223, v223
	v_lshlrev_b32_e32 v224, 16, v184
	v_and_b32_e32 v225, 0xffff0000, v184
	v_lshlrev_b32_e32 v226, 16, v185
	v_and_b32_e32 v227, 0xffff0000, v185
	v_lshlrev_b32_e32 v228, 16, v186
	v_and_b32_e32 v229, 0xffff0000, v186
	v_lshlrev_b32_e32 v230, 16, v187
	v_and_b32_e32 v231, 0xffff0000, v187
	s_add_u32 s56, s20, 0x141000
	s_addc_u32 s57, s21, 0
	global_load_dwordx4 v[184:187], v183, s[56:57]
	global_load_dwordx4 v[188:191], v183, s[56:57] offset:2048
	v_mul_f32_e32 v216, v216, v224
	v_mul_f32_e32 v217, v217, v225
	v_mul_f32_e32 v218, v218, v226
	v_mul_f32_e32 v219, v219, v227
	v_mul_f32_e32 v220, v220, v228
	v_mul_f32_e32 v221, v221, v229
	v_mul_f32_e32 v222, v222, v230
	v_mul_f32_e32 v223, v223, v231
	v_mul_f32_e32 v60, v60, v216
	v_mul_f32_e32 v61, v61, v217
	v_mul_f32_e32 v62, v62, v218
	v_mul_f32_e32 v63, v63, v219
	v_mul_f32_e32 v56, v56, v220
	v_mul_f32_e32 v57, v57, v221
	v_mul_f32_e32 v58, v58, v222
	v_mul_f32_e32 v59, v59, v223
	s_waitcnt vmcnt(6)
	v_lshlrev_b32_e32 v216, 16, v196
	v_and_b32_e32 v217, 0xffff0000, v196
	v_lshlrev_b32_e32 v218, 16, v197
	v_and_b32_e32 v219, 0xffff0000, v197
	v_lshlrev_b32_e32 v220, 16, v198
	v_and_b32_e32 v221, 0xffff0000, v198
	v_lshlrev_b32_e32 v222, 16, v199
	v_and_b32_e32 v223, 0xffff0000, v199
	v_rcp_f32_e32 v216, v216
	v_rcp_f32_e32 v217, v217
	v_rcp_f32_e32 v218, v218
	v_rcp_f32_e32 v219, v219
	v_rcp_f32_e32 v220, v220
	v_rcp_f32_e32 v221, v221
	v_rcp_f32_e32 v222, v222
	v_rcp_f32_e32 v223, v223
	v_lshlrev_b32_e32 v224, 16, v192
	v_and_b32_e32 v225, 0xffff0000, v192
	v_lshlrev_b32_e32 v226, 16, v193
	v_and_b32_e32 v227, 0xffff0000, v193
	v_lshlrev_b32_e32 v228, 16, v194
	v_and_b32_e32 v229, 0xffff0000, v194
	v_lshlrev_b32_e32 v230, 16, v195
	v_and_b32_e32 v231, 0xffff0000, v195
	global_load_dwordx4 v[192:195], v183, s[56:57] offset:256
	global_load_dwordx4 v[196:199], v183, s[56:57] offset:2304
	v_mul_f32_e32 v216, v216, v224
	v_mul_f32_e32 v217, v217, v225
	v_mul_f32_e32 v218, v218, v226
	v_mul_f32_e32 v219, v219, v227
	v_mul_f32_e32 v220, v220, v228
	v_mul_f32_e32 v221, v221, v229
	v_mul_f32_e32 v222, v222, v230
	v_mul_f32_e32 v223, v223, v231
	v_mul_f32_e32 v52, v52, v216
	v_mul_f32_e32 v53, v53, v217
	v_mul_f32_e32 v54, v54, v218
	v_mul_f32_e32 v55, v55, v219
	v_mul_f32_e32 v48, v48, v220
	v_mul_f32_e32 v49, v49, v221
	v_mul_f32_e32 v50, v50, v222
	v_mul_f32_e32 v51, v51, v223
	s_waitcnt vmcnt(6)
	v_lshlrev_b32_e32 v216, 16, v204
	v_and_b32_e32 v217, 0xffff0000, v204
	v_lshlrev_b32_e32 v218, 16, v205
	v_and_b32_e32 v219, 0xffff0000, v205
	v_lshlrev_b32_e32 v220, 16, v206
	v_and_b32_e32 v221, 0xffff0000, v206
	v_lshlrev_b32_e32 v222, 16, v207
	v_and_b32_e32 v223, 0xffff0000, v207
	v_rcp_f32_e32 v216, v216
	v_rcp_f32_e32 v217, v217
	v_rcp_f32_e32 v218, v218
	v_rcp_f32_e32 v219, v219
	v_rcp_f32_e32 v220, v220
	v_rcp_f32_e32 v221, v221
	v_rcp_f32_e32 v222, v222
	v_rcp_f32_e32 v223, v223
	v_lshlrev_b32_e32 v224, 16, v200
	v_and_b32_e32 v225, 0xffff0000, v200
	v_lshlrev_b32_e32 v226, 16, v201
	v_and_b32_e32 v227, 0xffff0000, v201
	v_lshlrev_b32_e32 v228, 16, v202
	v_and_b32_e32 v229, 0xffff0000, v202
	v_lshlrev_b32_e32 v230, 16, v203
	v_and_b32_e32 v231, 0xffff0000, v203
	s_add_u32 s56, s20, 0x161000
	s_addc_u32 s57, s21, 0
	global_load_dwordx4 v[200:203], v183, s[56:57]
	global_load_dwordx4 v[204:207], v183, s[56:57] offset:2048
	v_mul_f32_e32 v216, v216, v224
	v_mul_f32_e32 v217, v217, v225
	v_mul_f32_e32 v218, v218, v226
	v_mul_f32_e32 v219, v219, v227
	v_mul_f32_e32 v220, v220, v228
	v_mul_f32_e32 v221, v221, v229
	v_mul_f32_e32 v222, v222, v230
	v_mul_f32_e32 v223, v223, v231
	v_mul_f32_e32 v44, v44, v216
	v_mul_f32_e32 v45, v45, v217
	v_mul_f32_e32 v46, v46, v218
	v_mul_f32_e32 v47, v47, v219
	v_mul_f32_e32 v40, v40, v220
	v_mul_f32_e32 v41, v41, v221
	v_mul_f32_e32 v42, v42, v222
	v_mul_f32_e32 v43, v43, v223
	s_waitcnt vmcnt(6)
; __device__ __forceinline__ float bf_lo(unsigned w) { return __uint_as_float(w << 16); }
; __device__ __forceinline__ float bf_hi(unsigned w) { return __uint_as_float(w & 0xffff0000u); }
;     __device__ __forceinline__ void mid(Acc& acc, const Unit& u, int wr, int wc, int fr, int fq) const {
;         int row0 = u.pm * BM + wr * 64 + fr; const int col0 = u.pn * BM + wc * 32 + 8 * fq;
;         asm volatile("" : "+v"(row0));
; #pragma unroll
;         for (int ai = 0; ai < 2; ++ai)
; #pragma unroll
;             for (int m = 0; m < 4; ++m) {
;                 const int row = row0 + ai * HALF + m * 16;
; #pragma unroll
;                 for (int bj = 0; bj < 2; ++bj) {
;                     const int col = col0 + bj * HALF;
;                     const u32x4 ga = *(const u32x4*)(P + (size_t)row * PP + C_GA + col), gb = *(const u32x4*)(P + (size_t)row * PP + C_GB + col);
;                     const float ra[8] = {bf_lo(ga.x), bf_hi(ga.x), bf_lo(ga.y), bf_hi(ga.y), bf_lo(ga.z), bf_hi(ga.z), bf_lo(ga.w), bf_hi(ga.w)};
;                     const float rb[8] = {bf_lo(gb.x), bf_hi(gb.x), bf_lo(gb.y), bf_hi(gb.y), bf_lo(gb.z), bf_hi(gb.z), bf_lo(gb.w), bf_hi(gb.w)};
; #pragma unroll
;                     for (int n = 0; n < 2; ++n)
; #pragma unroll
;                         for (int e = 0; e < 4; ++e) acc[ai][bj][m][n][e] *= ra[4 * n + e] * __builtin_amdgcn_rcpf(rb[4 * n + e]);
;                 }
;                 asm volatile("" ::: "memory");
;             }
;     }
	v_lshlrev_b32_e32 v216, 16, v212
	v_and_b32_e32 v217, 0xffff0000, v212
	v_lshlrev_b32_e32 v218, 16, v213
	v_and_b32_e32 v219, 0xffff0000, v213
	v_lshlrev_b32_e32 v220, 16, v214
	v_and_b32_e32 v221, 0xffff0000, v214
	v_lshlrev_b32_e32 v222, 16, v215
	v_and_b32_e32 v223, 0xffff0000, v215
	v_rcp_f32_e32 v216, v216
	v_rcp_f32_e32 v217, v217
	v_rcp_f32_e32 v218, v218
	v_rcp_f32_e32 v219, v219
	v_rcp_f32_e32 v220, v220
	v_rcp_f32_e32 v221, v221
	v_rcp_f32_e32 v222, v222
	v_rcp_f32_e32 v223, v223
	v_lshlrev_b32_e32 v224, 16, v208
	v_and_b32_e32 v225, 0xffff0000, v208
	v_lshlrev_b32_e32 v226, 16, v209
	v_and_b32_e32 v227, 0xffff0000, v209
	v_lshlrev_b32_e32 v228, 16, v210
	v_and_b32_e32 v229, 0xffff0000, v210
	v_lshlrev_b32_e32 v230, 16, v211
	v_and_b32_e32 v231, 0xffff0000, v211
	global_load_dwordx4 v[208:211], v183, s[56:57] offset:256
	global_load_dwordx4 v[212:215], v183, s[56:57] offset:2304
	v_mul_f32_e32 v216, v216, v224
	v_mul_f32_e32 v217, v217, v225
	v_mul_f32_e32 v218, v218, v226
	v_mul_f32_e32 v219, v219, v227
	v_mul_f32_e32 v220, v220, v228
	v_mul_f32_e32 v221, v221, v229
	v_mul_f32_e32 v222, v222, v230
	v_mul_f32_e32 v223, v223, v231
	v_mul_f32_e32 v36, v36, v216
	v_mul_f32_e32 v37, v37, v217
	v_mul_f32_e32 v38, v38, v218
	v_mul_f32_e32 v39, v39, v219
	v_mul_f32_e32 v32, v32, v220
	v_mul_f32_e32 v33, v33, v221
	v_mul_f32_e32 v34, v34, v222
	v_mul_f32_e32 v35, v35, v223
	s_waitcnt vmcnt(6)
	v_lshlrev_b32_e32 v216, 16, v188
	v_and_b32_e32 v217, 0xffff0000, v188
	v_lshlrev_b32_e32 v218, 16, v189
	v_and_b32_e32 v219, 0xffff0000, v189
	v_lshlrev_b32_e32 v220, 16, v190
	v_and_b32_e32 v221, 0xffff0000, v190
	v_lshlrev_b32_e32 v222, 16, v191
	v_and_b32_e32 v223, 0xffff0000, v191
	v_rcp_f32_e32 v216, v216
	v_rcp_f32_e32 v217, v217
	v_rcp_f32_e32 v218, v218
	v_rcp_f32_e32 v219, v219
	v_rcp_f32_e32 v220, v220
	v_rcp_f32_e32 v221, v221
	v_rcp_f32_e32 v222, v222
	v_rcp_f32_e32 v223, v223
	v_lshlrev_b32_e32 v224, 16, v184
	v_and_b32_e32 v225, 0xffff0000, v184
	v_lshlrev_b32_e32 v226, 16, v185
	v_and_b32_e32 v227, 0xffff0000, v185
	v_lshlrev_b32_e32 v228, 16, v186
	v_and_b32_e32 v229, 0xffff0000, v186
	v_lshlrev_b32_e32 v230, 16, v187
	v_and_b32_e32 v231, 0xffff0000, v187
	v_mul_f32_e32 v216, v216, v224
	v_mul_f32_e32 v217, v217, v225
	v_mul_f32_e32 v218, v218, v226
	v_mul_f32_e32 v219, v219, v227
	v_mul_f32_e32 v220, v220, v228
	v_mul_f32_e32 v221, v221, v229
	v_mul_f32_e32 v222, v222, v230
	v_mul_f32_e32 v223, v223, v231
	v_mul_f32_e32 v28, v28, v216
	v_mul_f32_e32 v29, v29, v217
	v_mul_f32_e32 v30, v30, v218
	v_mul_f32_e32 v31, v31, v219
	v_mul_f32_e32 v24, v24, v220
	v_mul_f32_e32 v25, v25, v221
	v_mul_f32_e32 v26, v26, v222
	v_mul_f32_e32 v27, v27, v223
	s_waitcnt vmcnt(4)
	v_lshlrev_b32_e32 v216, 16, v196
	v_and_b32_e32 v217, 0xffff0000, v196
	v_lshlrev_b32_e32 v218, 16, v197
	v_and_b32_e32 v219, 0xffff0000, v197
	v_lshlrev_b32_e32 v220, 16, v198
	v_and_b32_e32 v221, 0xffff0000, v198
	v_lshlrev_b32_e32 v222, 16, v199
	v_and_b32_e32 v223, 0xffff0000, v199
	v_rcp_f32_e32 v216, v216
	v_rcp_f32_e32 v217, v217
	v_rcp_f32_e32 v218, v218
	v_rcp_f32_e32 v219, v219
	v_rcp_f32_e32 v220, v220
	v_rcp_f32_e32 v221, v221
	v_rcp_f32_e32 v222, v222
	v_rcp_f32_e32 v223, v223
	v_lshlrev_b32_e32 v224, 16, v192
	v_and_b32_e32 v225, 0xffff0000, v192
	v_lshlrev_b32_e32 v226, 16, v193
	v_and_b32_e32 v227, 0xffff0000, v193
	v_lshlrev_b32_e32 v228, 16, v194
	v_and_b32_e32 v229, 0xffff0000, v194
	v_lshlrev_b32_e32 v230, 16, v195
	v_and_b32_e32 v231, 0xffff0000, v195
	v_mul_f32_e32 v216, v216, v224
	v_mul_f32_e32 v217, v217, v225
	v_mul_f32_e32 v218, v218, v226
	v_mul_f32_e32 v219, v219, v227
	v_mul_f32_e32 v220, v220, v228
	v_mul_f32_e32 v221, v221, v229
	v_mul_f32_e32 v222, v222, v230
	v_mul_f32_e32 v223, v223, v231
	v_mul_f32_e32 v20, v20, v216
	v_mul_f32_e32 v21, v21, v217
	v_mul_f32_e32 v22, v22, v218
	v_mul_f32_e32 v23, v23, v219
	v_mul_f32_e32 v16, v16, v220
	v_mul_f32_e32 v17, v17, v221
	v_mul_f32_e32 v18, v18, v222
	v_mul_f32_e32 v19, v19, v223
	s_waitcnt vmcnt(2)
	v_lshlrev_b32_e32 v216, 16, v204
	v_and_b32_e32 v217, 0xffff0000, v204
	v_lshlrev_b32_e32 v218, 16, v205
	v_and_b32_e32 v219, 0xffff0000, v205
	v_lshlrev_b32_e32 v220, 16, v206
	v_and_b32_e32 v221, 0xffff0000, v206
	v_lshlrev_b32_e32 v222, 16, v207
	v_and_b32_e32 v223, 0xffff0000, v207
	v_rcp_f32_e32 v216, v216
	v_rcp_f32_e32 v217, v217
	v_rcp_f32_e32 v218, v218
	v_rcp_f32_e32 v219, v219
	v_rcp_f32_e32 v220, v220
	v_rcp_f32_e32 v221, v221
	v_rcp_f32_e32 v222, v222
	v_rcp_f32_e32 v223, v223
	v_lshlrev_b32_e32 v224, 16, v200
	v_and_b32_e32 v225, 0xffff0000, v200
	v_lshlrev_b32_e32 v226, 16, v201
	v_and_b32_e32 v227, 0xffff0000, v201
	v_lshlrev_b32_e32 v228, 16, v202
	v_and_b32_e32 v229, 0xffff0000, v202
	v_lshlrev_b32_e32 v230, 16, v203
	v_and_b32_e32 v231, 0xffff0000, v203
	v_mul_f32_e32 v216, v216, v224
	v_mul_f32_e32 v217, v217, v225
	v_mul_f32_e32 v218, v218, v226
	v_mul_f32_e32 v219, v219, v227
	v_mul_f32_e32 v220, v220, v228
	v_mul_f32_e32 v221, v221, v229
	v_mul_f32_e32 v222, v222, v230
	v_mul_f32_e32 v223, v223, v231
	v_mul_f32_e32 v12, v12, v216
	v_mul_f32_e32 v13, v13, v217
	v_mul_f32_e32 v14, v14, v218
	v_mul_f32_e32 v15, v15, v219
	v_mul_f32_e32 v8, v8, v220
	v_mul_f32_e32 v9, v9, v221
	v_mul_f32_e32 v10, v10, v222
	v_mul_f32_e32 v11, v11, v223
	s_waitcnt vmcnt(0)
	v_lshlrev_b32_e32 v216, 16, v212
	v_and_b32_e32 v217, 0xffff0000, v212
	v_lshlrev_b32_e32 v218, 16, v213
	v_and_b32_e32 v219, 0xffff0000, v213
	v_lshlrev_b32_e32 v220, 16, v214
	v_and_b32_e32 v221, 0xffff0000, v214
	v_lshlrev_b32_e32 v222, 16, v215
	v_and_b32_e32 v223, 0xffff0000, v215
	v_rcp_f32_e32 v216, v216
	v_rcp_f32_e32 v217, v217
	v_rcp_f32_e32 v218, v218
	v_rcp_f32_e32 v219, v219
	v_rcp_f32_e32 v220, v220
	v_rcp_f32_e32 v221, v221
	v_rcp_f32_e32 v222, v222
	v_rcp_f32_e32 v223, v223
	v_lshlrev_b32_e32 v224, 16, v208
	v_and_b32_e32 v225, 0xffff0000, v208
	v_lshlrev_b32_e32 v226, 16, v209
	v_and_b32_e32 v227, 0xffff0000, v209
	v_lshlrev_b32_e32 v228, 16, v210
	v_and_b32_e32 v229, 0xffff0000, v210
	v_lshlrev_b32_e32 v230, 16, v211
	v_and_b32_e32 v231, 0xffff0000, v211
	v_mul_f32_e32 v216, v216, v224
	v_mul_f32_e32 v217, v217, v225
	v_mul_f32_e32 v218, v218, v226
	v_mul_f32_e32 v219, v219, v227
	v_mul_f32_e32 v220, v220, v228
	v_mul_f32_e32 v221, v221, v229
	v_mul_f32_e32 v222, v222, v230
	v_mul_f32_e32 v223, v223, v231
	v_mul_f32_e32 v4, v4, v216
	v_mul_f32_e32 v5, v5, v217
	v_mul_f32_e32 v6, v6, v218
	v_mul_f32_e32 v7, v7, v219
	v_mul_f32_e32 v0, v0, v220
	v_mul_f32_e32 v1, v1, v221
	v_mul_f32_e32 v2, v2, v222
	v_mul_f32_e32 v3, v3, v223
	s_branch .LBB0_1083
